# attention unit prologues: bias-row load no longer waited alone; its LDS table writes moved after the Q/K/V (diff) or kmean (MoBA) wait
# speedup vs baseline: 1.0174x; 1.0010x over previous
; __device__ __forceinline__ void diff_unit(int b, int hd, int qb, const bf16_t* Q, const bf16_t* K, const bf16_t* VT, bf16_t* O, const float* biasd, float lam, const float* subg, ALAS unsigned char* lds) {
;     ...
;     const int tid = tid_, lane = tid & 63, wid = __builtin_amdgcn_readfirstlane(tid >> 6), r32 = lane & 31, hi = lane >> 5;
;     const int map = wid >> 2, w4 = wid & 3, q0 = qb * 128 + w4 * 32, qpos = q0 + r32;
;     if (wid >= 4) __builtin_amdgcn_s_setprio(1);
;     const size_t tok0 = (size_t)b * SEQ;
;     ALAS float* btab = (ALAS float*)(lds + 73728);
;     btab[tid] = biasd[(2 * hd) * 256 + tid];
;     const ALAS float* bt = btab + map * 256;
;     const float cb = biasd[(2 * hd + map) * 256 + 255];
;     bf16x8 qf[4];
;     { const bf16_t* qp = Q + (tok0 + qpos) * 1024 + (2 * hd + map) * 64 + hi * 8;
; #pragma unroll
;       for (int d0 = 0; d0 < 4; ++d0) qf[d0] = *(const bf16x8*)(qp + d0 * 16); }
;     const int NT = 2 * (qb + 1);
;     const bf16_t* kg[2]; const bf16_t* vg[2]; int kl[2], vl[2];
; #pragma unroll
;     for (int i = 0; i < 2; ++i) { const int c = tid + 512 * i; const int key = c >> 4, part = c & 15;
;         kg[i] = K + (tok0 + key) * 1024 + hd * 128 + part * 8; kl[i] = ((part >> 3) * 64 + key) * ROWB + (part & 7) * 16;
;         const int d = c >> 3, pv = c & 7; vg[i] = VT + (size_t)(hd * 128 + d) * MTOK + tok0 + pv * 8; vl[i] = 18432 + d * ROWB + pv * 16; }
;     u32x4 kr[2], vr[2];
; #pragma unroll
;     for (int i = 0; i < 2; ++i) { kr[i] = *(const u32x4*)(kg[i]); vr[i] = *(const u32x4*)(vg[i]); }
;     f32x16 o[4]; float mref = 0.f, lsum = 0.f;
; #pragma unroll
;     for (int d = 0; d < 4; ++d)
; #pragma unroll
;         for (int r = 0; r < 16; ++r) o[d][r] = 0.f;
;     for (int t = 0; t < NT; ++t) {
;         ALAS unsigned char* buf = lds + (t & 1) * 36864;
; #pragma unroll
;         for (int i = 0; i < 2; ++i) { *(ALAS u32x4*)(buf + kl[i]) = kr[i]; *(ALAS u32x4*)(buf + vl[i]) = vr[i]; }
;         __syncthreads();
;         if (t + 1 < NT) {
; #pragma unroll
;             for (int i = 0; i < 2; ++i) { kr[i] = *(const u32x4*)(kg[i] + (size_t)(t + 1) * 64 * 1024); vr[i] = *(const u32x4*)(vg[i] + (t + 1) * 64); }
;         }
;         const int kbase = 64 * t;
;         if (kbase <= q0 + 31) {
;             const bool far = (q0 - (kbase + 63)) >= 128;
;             f32x16 s0, s1; const float ci = (far ? cb : 0.f) - mref;
.LBB0_497:
	s_ashr_i32 s9, s1, 6
	s_and_b32 s6, s1, 3
	s_and_b32 s9, s9, -8
	s_or_b32 s6, s9, s6
	s_and_b32 s8, s1, 0x100
	s_xor_b32 s9, s6, 7
	s_cmp_eq_u32 s8, 0
	s_cselect_b32 s14, s6, s9
	s_bfe_u32 s10, s1, 0x30002
	v_lshl_add_u32 v0, s10, 9, v135
	v_ashrrev_i32_e32 v1, 31, v0
	v_lshl_add_u64 v[0:1], v[0:1], 2, s[96:97]
	global_load_dword v26, v[0:1], off
	s_and_b32 s8, s4, 3
	s_lshl_b32 s12, s14, 7
	s_lshl_b32 s13, s8, 5
	v_and_b32_e32 v70, 31, v135
	s_or_b32 s15, s13, s12
	v_or_b32_e32 v136, s15, v70
	s_lshl_b32 s4, s1, 7
	v_lshl_add_u32 v27, v135, 2, 0
	s_and_b32 s4, s4, 0x7000
	v_add_u32_e32 v27, 0x12000, v27
	v_ashrrev_i32_e32 v137, 31, v136
	v_bfe_u32 v2, v135, 5, 1
	s_ashr_i32 s9, s7, 8
	s_lshl_b32 s6, s10, 7
	s_cmp_lt_i32 s14, 0
	v_lshlrev_b32_e32 v134, 3, v2
	v_lshlrev_b32_e32 v130, 4, v2
	v_lshrrev_b32_e32 v28, 8, v135
	v_lshl_add_u32 v28, v28, 10, v27
	v_lshl_add_u64 v[0:1], v[136:137], 0, s[4:5]
	v_lshlrev_b64 v[132:133], 10, v[0:1]
	s_cbranch_scc1 .LBB0_511
	s_lshl_b32 s10, s10, 1
	s_add_i32 s17, s9, s10
	s_lshl_b32 s10, s17, 8
	s_ashr_i32 s11, s10, 31
	s_and_b32 s16, s7, 0x3fffff00
	s_lshl_b64 s[10:11], s[10:11], 2
	s_add_u32 s10, s96, s10
	s_addc_u32 s11, s97, s11
	global_load_dword v137, v145, s[10:11] offset:1020
	s_lshl_b32 s10, s6, 1
	s_add_u32 s10, s82, s10
	v_lshlrev_b32_e32 v1, 4, v135
	s_addc_u32 s11, s83, 0
	v_and_b32_e32 v144, 0xf0, v1
	v_lshlrev_b32_e32 v0, 3, v135
	v_lshl_add_u64 v[2:3], s[10:11], 0, v[144:145]
	s_lshl_b32 s10, s4, 1
	v_and_b32_e32 v8, 64, v0
	s_add_u32 s10, s20, s10
	v_ashrrev_i32_e32 v64, 4, v135
	v_and_b32_e32 v20, 0x70, v1
	s_addc_u32 s11, s21, 0
	v_mov_b32_e32 v21, v145
	v_add_u32_e32 v6, v8, v64
	s_movk_i32 s18, 0x90
	v_lshl_add_u64 v[4:5], s[10:11], 0, v[20:21]
	v_mad_u64_u32 v[138:139], s[10:11], v6, s18, v[20:21]
	v_ashrrev_i32_e32 v21, 3, v135
	v_add_u32_e32 v6, s6, v21
	v_add_u32_e32 v9, 0x200, v135
	v_ashrrev_i32_e32 v7, 31, v6
	v_ashrrev_i32_e32 v66, 4, v9
	v_ashrrev_i32_e32 v65, 31, v64
	v_lshlrev_b64 v[6:7], 16, v[6:7]
	v_ashrrev_i32_e32 v67, 31, v66
	v_lshl_add_u64 v[0:1], v[64:65], 0, s[4:5]
	v_lshl_add_u64 v[140:141], v[4:5], 0, v[6:7]
	v_lshl_add_u64 v[6:7], v[66:67], 0, s[4:5]
	v_lshlrev_b64 v[0:1], 11, v[0:1]
	v_lshlrev_b64 v[6:7], 11, v[6:7]
	v_lshl_add_u64 v[0:1], v[2:3], 0, v[0:1]
	v_lshl_add_u64 v[2:3], v[2:3], 0, v[6:7]
	v_add_u32_e32 v6, v66, v8
	v_ashrrev_i32_e32 v22, 3, v9
	v_mad_u64_u32 v[142:143], s[10:11], v6, s18, v[20:21]
	v_add_u32_e32 v6, s6, v22
	v_ashrrev_i32_e32 v7, 31, v6
	v_lshlrev_b64 v[6:7], 16, v[6:7]
	s_lshl_b32 s4, s16, 2
	s_lshl_b32 s16, s17, 6
	v_lshl_add_u64 v[156:157], v[4:5], 0, v[6:7]
	v_lshl_add_u64 v[4:5], v[132:133], 1, s[80:81]
	s_ashr_i32 s17, s16, 31
	v_lshl_add_u64 v[4:5], s[16:17], 1, v[4:5]
	v_mov_b32_e32 v131, v145
	v_lshl_add_u64 v[4:5], v[4:5], 0, v[130:131]
	global_load_dwordx4 v[96:99], v[4:5], off offset:96
	global_load_dwordx4 v[100:103], v[4:5], off offset:64
	global_load_dwordx4 v[104:107], v[4:5], off offset:32
	global_load_dwordx4 v[108:111], v[4:5], off
	s_nop 0
	global_load_dwordx4 v[4:7], v[156:157], off
	global_load_dwordx4 v[8:11], v[2:3], off
	global_load_dwordx4 v[12:15], v[140:141], off
	global_load_dwordx4 v[16:19], v[0:1], off
	v_lshlrev_b32_e32 v24, 1, v70
	v_lshrrev_b32_e32 v25, 1, v135
	v_and_b32_e32 v23, 19, v135
	v_and_b32_e32 v24, 8, v24
	v_and_b32_e32 v25, 4, v25
	v_or3_b32 v23, v25, v23, v24
	v_mul_u32_u24_e32 v139, 0x90, v23
	v_add_u32_e32 v23, 0, v138
	v_mad_u64_u32 v[158:159], s[16:17], v21, s18, v[20:21]
	s_add_i32 s10, s4, 0
	s_mov_b32 s4, 0x20000
	v_mad_u64_u32 v[160:161], s[16:17], v22, s18, v[20:21]
	v_add_co_u32_e32 v0, vcc, s4, v0
	s_add_i32 s10, s10, 0x12000
	s_nop 0
	v_addc_co_u32_e32 v1, vcc, 0, v1, vcc
	s_mul_i32 s11, s9, 0x2400
	s_cmpk_gt_i32 s15, 0xbe
	s_waitcnt vmcnt(0)
	ds_write_b32 v27, v26
	ds_write_b32 v28, v26 offset:3072
	ds_write_b32 v28, v205 offset:2048
	ds_write_b128 v23, v[16:19]
	v_add_u32_e32 v16, 0, v158
	ds_write_b128 v16, v[12:15] offset:18432
	v_add_u32_e32 v12, 0, v142
	ds_write_b128 v12, v[8:11]
	v_add_u32_e32 v8, 0, v160
	ds_write_b128 v8, v[4:7] offset:18432
	s_waitcnt lgkmcnt(0)
	s_barrier
	global_load_dwordx4 v[112:115], v[0:1], off
	global_load_dwordx4 v[116:119], v[140:141], off offset:128
	v_add_co_u32_e32 v0, vcc, s4, v2
	s_nop 1
	v_addc_co_u32_e32 v1, vcc, 0, v3, vcc
	global_load_dwordx4 v[120:123], v[0:1], off
	global_load_dwordx4 v[124:127], v[156:157], off offset:128
	s_cselect_b64 vcc, -1, 0
	s_add_i32 s4, s11, 0
	v_add3_u32 v1, s4, v139, v130
	ds_read_b128 v[32:35], v1 offset:0
	ds_read_b128 v[36:39], v1 offset:4608
	ds_read_b128 v[40:43], v1 offset:32
	ds_read_b128 v[44:47], v1 offset:4640
	ds_read_b128 v[48:51], v1 offset:64
	ds_read_b128 v[52:55], v1 offset:4672
	ds_read_b128 v[56:59], v1 offset:96
	ds_read_b128 v[60:63], v1 offset:4704
	v_cndmask_b32_e32 v0, 0, v137, vcc
	v_mov_b32_e32 v1, v0
	v_mov_b32_e32 v2, v0
	v_mov_b32_e32 v3, v0
	v_mov_b32_e32 v4, v0
	v_mov_b32_e32 v5, v0
	v_mov_b32_e32 v6, v0
	v_mov_b32_e32 v7, v0
	v_mov_b32_e32 v8, v0
	v_mov_b32_e32 v9, v0
	v_mov_b32_e32 v10, v0
	v_mov_b32_e32 v11, v0
	v_mov_b32_e32 v12, v0
	v_mov_b32_e32 v13, v0
	v_mov_b32_e32 v14, v0
	v_mov_b32_e32 v15, v0
	s_waitcnt lgkmcnt(6)
	s_nop 1
	v_mfma_f32_32x32x16_bf16 v[16:31], v[32:35], v[108:111], v[0:15]
	s_and_b64 vcc, exec, vcc
	v_mfma_f32_32x32x16_bf16 v[0:15], v[36:39], v[108:111], v[0:15]
	s_waitcnt lgkmcnt(4)
	v_mfma_f32_32x32x16_bf16 v[16:31], v[40:43], v[104:107], v[16:31]
	v_mfma_f32_32x32x16_bf16 v[0:15], v[44:47], v[104:107], v[0:15]
	s_waitcnt lgkmcnt(2)
	v_mfma_f32_32x32x16_bf16 v[16:31], v[48:51], v[100:103], v[16:31]
	v_mfma_f32_32x32x16_bf16 v[0:15], v[52:55], v[100:103], v[0:15]
	s_waitcnt lgkmcnt(0)
	v_mfma_f32_32x32x16_bf16 v[16:31], v[56:59], v[96:99], v[16:31]
	v_mfma_f32_32x32x16_bf16 v[0:15], v[60:63], v[96:99], v[0:15]
	s_cbranch_vccnz .LBB0_500
; #define ALAS __attribute__((address_space(3)))
; __device__ __forceinline__ void near_bias(f32x16& s0, f32x16& s1, const ALAS float* bt, int qpos, int kbase, int hi) {
; #pragma unroll
;     for (int r = 0; r < 16; ++r) {
;         const int d0 = qpos - (kbase + (r & 7) + 8 * hi + 16 * (r >> 3)), d1 = d0 - 32;
;         const float b0 = bt[min(max(d0, 0), 255)], b1 = bt[min(max(d1, 0), 255)];
;         s0[r] = d0 < 0 ? NEG : s0[r] + b0; s1[r] = d1 < 0 ? NEG : s1[r] + b1;
;     }
; }
	v_xad_u32 v69, v134, -1, v136
	v_med3_i32 v34, v69, 0, v204
	v_lshl_add_u32 v35, v34, 2, s10
	v_max_i32_e32 v34, 32, v69
	v_subrev_u32_e32 v34, 32, v34
	v_min_u32_e32 v34, 0xff, v34
	v_or_b32_e32 v37, 2, v134
	v_lshl_add_u32 v36, v34, 2, s10
	v_or_b32_e32 v34, 3, v134
	v_sub_u32_e32 v72, v136, v37
	v_sub_u32_e32 v71, v136, v34
	v_med3_i32 v34, v72, 0, v204
	v_lshl_add_u32 v37, v34, 2, s10
	v_max_i32_e32 v34, 32, v72
	v_subrev_u32_e32 v34, 32, v34
	v_min_u32_e32 v34, 0xff, v34
	v_sub_u32_e32 v68, v136, v134
	v_lshl_add_u32 v38, v34, 2, s10
	v_max_i32_e32 v34, 32, v71
	v_max_i32_e32 v33, 32, v68
	v_subrev_u32_e32 v34, 32, v34
	v_subrev_u32_e32 v33, 32, v33
	v_min_u32_e32 v34, 0xff, v34
	v_med3_i32 v32, v68, 0, v204
	v_min_u32_e32 v33, 0xff, v33
	v_lshl_add_u32 v39, v34, 2, s10
	v_med3_i32 v34, v71, 0, v204
	v_lshl_add_u32 v32, v32, 2, s10
	v_lshl_add_u32 v33, v33, 2, s10
	v_lshl_add_u32 v40, v34, 2, s10
	ds_read_b32 v34, v32
	ds_read_b32 v32, v33
	ds_read_b32 v35, v35
	ds_read_b32 v33, v36
	ds_read_b32 v36, v37
	ds_read_b32 v38, v38
	ds_read_b32 v39, v39
	ds_read_b32 v37, v40
	v_or_b32_e32 v40, 5, v134
	v_sub_u32_e32 v73, v136, v40
	v_max_i32_e32 v42, 32, v73
	v_subrev_u32_e32 v42, 32, v42
	v_min_u32_e32 v42, 0xff, v42
	v_lshl_add_u32 v43, v42, 2, s10
	v_med3_i32 v42, v73, 0, v204
	v_or_b32_e32 v45, 6, v134
	v_lshl_add_u32 v44, v42, 2, s10
	v_or_b32_e32 v42, 7, v134
	v_sub_u32_e32 v76, v136, v45
	v_sub_u32_e32 v75, v136, v42
	v_med3_i32 v42, v76, 0, v204
	v_lshl_add_u32 v45, v42, 2, s10
	v_max_i32_e32 v42, 32, v76
	v_subrev_u32_e32 v42, 32, v42
	v_or_b32_e32 v41, 4, v134
	v_min_u32_e32 v42, 0xff, v42
	v_sub_u32_e32 v74, v136, v41
	v_lshl_add_u32 v46, v42, 2, s10
	v_max_i32_e32 v42, 32, v75
	v_max_i32_e32 v41, 32, v74
	v_subrev_u32_e32 v42, 32, v42
	v_subrev_u32_e32 v41, 32, v41
	v_min_u32_e32 v42, 0xff, v42
	v_med3_i32 v40, v74, 0, v204
	v_min_u32_e32 v41, 0xff, v41
	v_lshl_add_u32 v47, v42, 2, s10
	v_med3_i32 v42, v75, 0, v204
	v_lshl_add_u32 v40, v40, 2, s10
	v_lshl_add_u32 v41, v41, 2, s10
	v_lshl_add_u32 v48, v42, 2, s10
	ds_read_b32 v40, v40
	ds_read_b32 v42, v41
	ds_read_b32 v43, v43
	ds_read_b32 v41, v44
	ds_read_b32 v44, v45
	ds_read_b32 v46, v46
	ds_read_b32 v47, v47
	ds_read_b32 v45, v48
	v_or_b32_e32 v48, 17, v134
	v_sub_u32_e32 v77, v136, v48
	v_max_i32_e32 v50, 32, v77
	v_subrev_u32_e32 v50, 32, v50
	v_min_u32_e32 v50, 0xff, v50
	v_lshl_add_u32 v51, v50, 2, s10
	v_med3_i32 v50, v77, 0, v204
	v_or_b32_e32 v53, 18, v134
	v_lshl_add_u32 v52, v50, 2, s10
	v_or_b32_e32 v50, 19, v134
	v_sub_u32_e32 v80, v136, v53
	v_sub_u32_e32 v79, v136, v50
	v_med3_i32 v50, v80, 0, v204
	v_lshl_add_u32 v53, v50, 2, s10
	v_max_i32_e32 v50, 32, v80
	v_subrev_u32_e32 v50, 32, v50
	v_or_b32_e32 v49, 16, v134
	v_min_u32_e32 v50, 0xff, v50
	v_sub_u32_e32 v78, v136, v49
	v_lshl_add_u32 v54, v50, 2, s10
	v_max_i32_e32 v50, 32, v79
	v_max_i32_e32 v49, 32, v78
	v_subrev_u32_e32 v50, 32, v50
	v_subrev_u32_e32 v49, 32, v49
	v_min_u32_e32 v50, 0xff, v50
	v_med3_i32 v48, v78, 0, v204
	v_min_u32_e32 v49, 0xff, v49
	v_lshl_add_u32 v55, v50, 2, s10
	v_med3_i32 v50, v79, 0, v204
	v_lshl_add_u32 v48, v48, 2, s10
	v_lshl_add_u32 v49, v49, 2, s10
	v_lshl_add_u32 v56, v50, 2, s10
	ds_read_b32 v48, v48
	ds_read_b32 v50, v49
	ds_read_b32 v51, v51
	ds_read_b32 v49, v52
	ds_read_b32 v52, v53
	ds_read_b32 v54, v54
	ds_read_b32 v55, v55
	ds_read_b32 v53, v56
	v_or_b32_e32 v56, 21, v134
	v_sub_u32_e32 v81, v136, v56
	v_max_i32_e32 v58, 32, v81
	v_subrev_u32_e32 v58, 32, v58
	v_min_u32_e32 v58, 0xff, v58
	v_lshl_add_u32 v59, v58, 2, s10
	v_med3_i32 v58, v81, 0, v204
	v_or_b32_e32 v61, 22, v134
	v_lshl_add_u32 v60, v58, 2, s10
	v_or_b32_e32 v58, 23, v134
	v_sub_u32_e32 v84, v136, v61
	v_sub_u32_e32 v83, v136, v58
	v_med3_i32 v58, v84, 0, v204
	v_lshl_add_u32 v61, v58, 2, s10
	v_max_i32_e32 v58, 32, v84
	v_or_b32_e32 v57, 20, v134
	v_subrev_u32_e32 v58, 32, v58
	v_sub_u32_e32 v82, v136, v57
	v_min_u32_e32 v58, 0xff, v58
	v_max_i32_e32 v57, 32, v82
	v_lshl_add_u32 v62, v58, 2, s10
	v_max_i32_e32 v58, 32, v83
	v_subrev_u32_e32 v57, 32, v57
	v_subrev_u32_e32 v58, 32, v58
	v_med3_i32 v56, v82, 0, v204
	v_min_u32_e32 v57, 0xff, v57
	v_min_u32_e32 v58, 0xff, v58
	v_lshl_add_u32 v56, v56, 2, s10
	v_lshl_add_u32 v57, v57, 2, s10
	v_lshl_add_u32 v63, v58, 2, s10
	v_med3_i32 v58, v83, 0, v204
	v_lshl_add_u32 v85, v58, 2, s10
	ds_read_b32 v56, v56
	ds_read_b32 v58, v57
	ds_read_b32 v59, v59
	ds_read_b32 v57, v60
	ds_read_b32 v60, v61
	ds_read_b32 v62, v62
	ds_read_b32 v63, v63
	ds_read_b32 v61, v85
	s_waitcnt lgkmcnt(14)
; __device__ __forceinline__ void near_bias(f32x16& s0, f32x16& s1, const ALAS float* bt, int qpos, int kbase, int hi) {
;     ...
;     for (int r = 0; r < 16; ++r) {
;         const int d0 = qpos - (kbase + (r & 7) + 8 * hi + 16 * (r >> 3)), d1 = d0 - 32;
;         const float b0 = bt[min(max(d0, 0), 255)], b1 = bt[min(max(d1, 0), 255)];
;         s0[r] = d0 < 0 ? NEG : s0[r] + b0; s1[r] = d1 < 0 ? NEG : s1[r] + b1;
;     }
	v_pk_add_f32 v[16:17], v[16:17], v[34:35]
	v_cmp_lt_i32_e32 vcc, -1, v69
	s_waitcnt lgkmcnt(4)
	v_pk_add_f32 v[28:29], v[28:29], v[56:57]
	v_pk_add_f32 v[26:27], v[26:27], v[52:53]
	s_waitcnt lgkmcnt(0)
	v_pk_add_f32 v[30:31], v[30:31], v[60:61]
	v_cndmask_b32_e32 v17, v205, v17, vcc
	v_cmp_lt_i32_e32 vcc, -1, v83
	v_pk_add_f32 v[24:25], v[24:25], v[48:49]
	v_pk_add_f32 v[22:23], v[22:23], v[44:45]
	v_cndmask_b32_e32 v31, v205, v31, vcc
	v_cmp_lt_i32_e32 vcc, -1, v84
	v_pk_add_f32 v[20:21], v[20:21], v[40:41]
	v_pk_add_f32 v[18:19], v[18:19], v[36:37]
	v_cndmask_b32_e32 v30, v205, v30, vcc
	v_cmp_lt_i32_e32 vcc, -1, v81
	v_pk_add_f32 v[0:1], v[0:1], v[32:33]
	v_pk_add_f32 v[14:15], v[14:15], v[62:63]
	v_cndmask_b32_e32 v29, v205, v29, vcc
	v_cmp_lt_i32_e32 vcc, -1, v82
	v_pk_add_f32 v[12:13], v[12:13], v[58:59]
	v_pk_add_f32 v[10:11], v[10:11], v[54:55]
	v_cndmask_b32_e32 v28, v205, v28, vcc
	v_cmp_lt_i32_e32 vcc, -1, v79
	v_pk_add_f32 v[8:9], v[8:9], v[50:51]
	v_pk_add_f32 v[6:7], v[6:7], v[46:47]
	v_cndmask_b32_e32 v27, v205, v27, vcc
	v_cmp_lt_i32_e32 vcc, -1, v80
	v_pk_add_f32 v[4:5], v[4:5], v[42:43]
	v_pk_add_f32 v[2:3], v[2:3], v[38:39]
	v_cndmask_b32_e32 v26, v205, v26, vcc
	v_cmp_lt_i32_e32 vcc, -1, v77
	s_nop 1
	v_cndmask_b32_e32 v25, v205, v25, vcc
	v_cmp_lt_i32_e32 vcc, -1, v78
	s_nop 1
	v_cndmask_b32_e32 v24, v205, v24, vcc
	v_cmp_lt_i32_e32 vcc, -1, v75
	s_nop 1
	v_cndmask_b32_e32 v23, v205, v23, vcc
	v_cmp_lt_i32_e32 vcc, -1, v76
	s_nop 1
	v_cndmask_b32_e32 v22, v205, v22, vcc
	v_cmp_lt_i32_e32 vcc, -1, v73
	s_nop 1
	v_cndmask_b32_e32 v21, v205, v21, vcc
	v_cmp_lt_i32_e32 vcc, -1, v74
	s_nop 1
	v_cndmask_b32_e32 v20, v205, v20, vcc
	v_cmp_lt_i32_e32 vcc, -1, v71
	s_nop 1
	v_cndmask_b32_e32 v19, v205, v19, vcc
	v_cmp_lt_i32_e32 vcc, -1, v72
	s_nop 1
	v_cndmask_b32_e32 v18, v205, v18, vcc
	v_cmp_lt_i32_e32 vcc, -1, v68
	s_nop 1
	v_cndmask_b32_e32 v16, v205, v16, vcc
	v_cmp_lt_i32_e32 vcc, 31, v69
	s_nop 1
	v_cndmask_b32_e32 v1, v205, v1, vcc
	v_cmp_lt_i32_e32 vcc, 31, v83
	s_nop 1
	v_cndmask_b32_e32 v15, v205, v15, vcc
	v_cmp_lt_i32_e32 vcc, 31, v84
	s_nop 1
	v_cndmask_b32_e32 v14, v205, v14, vcc
	v_cmp_lt_i32_e32 vcc, 31, v81
	s_nop 1
	v_cndmask_b32_e32 v13, v205, v13, vcc
	v_cmp_lt_i32_e32 vcc, 31, v82
	s_nop 1
	v_cndmask_b32_e32 v12, v205, v12, vcc
	v_cmp_lt_i32_e32 vcc, 31, v79
	s_nop 1
	v_cndmask_b32_e32 v11, v205, v11, vcc
	v_cmp_lt_i32_e32 vcc, 31, v80
	s_nop 1
	v_cndmask_b32_e32 v10, v205, v10, vcc
	v_cmp_lt_i32_e32 vcc, 31, v77
	s_nop 1
	v_cndmask_b32_e32 v9, v205, v9, vcc
	v_cmp_lt_i32_e32 vcc, 31, v78
	s_nop 1
	v_cndmask_b32_e32 v8, v205, v8, vcc
	v_cmp_lt_i32_e32 vcc, 31, v75
	s_nop 1
	v_cndmask_b32_e32 v7, v205, v7, vcc
	v_cmp_lt_i32_e32 vcc, 31, v76
	s_nop 1
	v_cndmask_b32_e32 v6, v205, v6, vcc
	v_cmp_lt_i32_e32 vcc, 31, v73
	s_nop 1
	v_cndmask_b32_e32 v5, v205, v5, vcc
	v_cmp_lt_i32_e32 vcc, 31, v74
	s_nop 1
	v_cndmask_b32_e32 v4, v205, v4, vcc
	v_cmp_lt_i32_e32 vcc, 31, v71
	s_nop 1
	v_cndmask_b32_e32 v3, v205, v3, vcc
	v_cmp_lt_i32_e32 vcc, 31, v72
	s_nop 1
	v_cndmask_b32_e32 v2, v205, v2, vcc
	v_cmp_lt_i32_e32 vcc, 31, v68
	s_nop 1
	v_cndmask_b32_e32 v0, v205, v0, vcc

; __device__ __forceinline__ void diff_unit(int b, int hd, int qb, const bf16_t* Q, const bf16_t* K, const bf16_t* VT, bf16_t* O, const float* biasd, float lam, const float* subg, ALAS unsigned char* lds) {
;     ...
;     f32x16 o[4]; float mref = 0.f, lsum = 0.f;
; #pragma unroll
;     for (int d = 0; d < 4; ++d)
; #pragma unroll
;         for (int r = 0; r < 16; ++r) o[d][r] = 0.f;
.LBB0_511:
	s_waitcnt vmcnt(0)
	v_mov_b32_e32 v63, 0
	v_mov_b32_e32 v62, 0
	v_mov_b32_e32 v61, 0
	v_mov_b32_e32 v60, 0
	v_mov_b32_e32 v59, 0
	v_mov_b32_e32 v58, 0
	v_mov_b32_e32 v57, 0
	v_mov_b32_e32 v56, 0
	v_mov_b32_e32 v55, 0
	v_mov_b32_e32 v54, 0
	v_mov_b32_e32 v53, 0
	v_mov_b32_e32 v52, 0
	v_mov_b32_e32 v51, 0
	v_mov_b32_e32 v50, 0
	v_mov_b32_e32 v49, 0
	v_mov_b32_e32 v48, 0
	v_mov_b32_e32 v47, 0
	v_mov_b32_e32 v46, 0
	v_mov_b32_e32 v45, 0
	v_mov_b32_e32 v44, 0
	v_mov_b32_e32 v43, 0
	v_mov_b32_e32 v42, 0
	v_mov_b32_e32 v41, 0
	v_mov_b32_e32 v40, 0
	v_mov_b32_e32 v39, 0
	v_mov_b32_e32 v38, 0
	v_mov_b32_e32 v37, 0
	v_mov_b32_e32 v36, 0
	v_mov_b32_e32 v35, 0
	v_mov_b32_e32 v34, 0
	v_mov_b32_e32 v33, 0
	v_mov_b32_e32 v32, 0
	v_mov_b32_e32 v31, 0
	v_mov_b32_e32 v30, 0
	v_mov_b32_e32 v29, 0
	v_mov_b32_e32 v28, 0
	v_mov_b32_e32 v27, 0
	v_mov_b32_e32 v26, 0
	v_mov_b32_e32 v25, 0
	v_mov_b32_e32 v24, 0
	v_mov_b32_e32 v23, 0
	v_mov_b32_e32 v22, 0
	v_mov_b32_e32 v21, 0
	v_mov_b32_e32 v20, 0
	v_mov_b32_e32 v19, 0
	v_mov_b32_e32 v18, 0
	v_mov_b32_e32 v17, 0
	v_mov_b32_e32 v16, 0
	v_mov_b32_e32 v15, 0
	v_mov_b32_e32 v14, 0
	v_mov_b32_e32 v13, 0
	v_mov_b32_e32 v12, 0
	v_mov_b32_e32 v11, 0
	v_mov_b32_e32 v10, 0
	v_mov_b32_e32 v9, 0
	v_mov_b32_e32 v8, 0
	v_mov_b32_e32 v7, 0
	v_mov_b32_e32 v6, 0
	v_mov_b32_e32 v5, 0
	v_mov_b32_e32 v4, 0
	v_mov_b32_e32 v3, 0
	v_mov_b32_e32 v2, 0
	v_mov_b32_e32 v1, 0
	v_mov_b32_e32 v0, 0
	v_mov_b32_e32 v162, 0

; #define ALAS __attribute__((address_space(3)))
; __device__ __forceinline__ void moba_unit(int b, int h, int j, const bf16_t* Q, const bf16_t* K, const bf16_t* VT, bf16_t* O, const float* biasd, const float* kmean, ALAS unsigned char* lds) {
;     ...
;     if (wid >= 4) __builtin_amdgcn_s_setprio(1);
;     const size_t tok0 = (size_t)b * SEQ;
;     ALAS float* bt = (ALAS float*)(lds + 36864);
;     if (tid < 256) bt[tid] = biasd[h * 256 + tid];
;     const float cb = biasd[h * 256 + 255];
;     { const int n = tid >> 5, d2 = (tid & 31) * 2; const float* kmp = kmean + (size_t)(b * 16 + n) * 2048 + h * 64 + d2; const float v0 = kmp[0] + kmp[1024], v1 = kmp[1] + kmp[1025];
;       const unsigned wh = cvtpk(v0, v1); const float h0 = __uint_as_float(wh << 16), h1 = __uint_as_float(wh & 0xffff0000u); const unsigned wl = cvtpk(v0 - h0, v1 - h1);
;       *(ALAS unsigned*)(lds + 37888 + n * ROWB + d2 * 2) = wh; *(ALAS unsigned*)(lds + 40192 + n * ROWB + d2 * 2) = wl; }
;     bf16x8 qf[4];
;     { const bf16_t* qp = Q + (tok0 + qpos) * 1024 + h * 64 + hi * 8;
; #pragma unroll
;       for (int d0 = 0; d0 < 4; ++d0) qf[d0] = *(const bf16x8*)(qp + d0 * 16); }
;     const int NT = 4 * (j + 1);
;     const int key = tid >> 3, part = tid & 7;
;     const bf16_t* kg = K + (tok0 + key) * 1024 + h * 64 + part * 8; const int kl = key * ROWB + part * 16;
;     const bf16_t* vg = VT + (size_t)(h * 64 + key) * MTOK + tok0 + part * 8; const int vl = 9216 + key * ROWB + part * 16;
;     u32x4 kr, vr;
;     { const int kb0 = 256 * j; kr = *(const u32x4*)(kg + (size_t)kb0 * 1024); vr = *(const u32x4*)(vg + kb0); }
;     __syncthreads();
;     unsigned selmask = 0u;
;     {
;         f32x16 g;
; #pragma unroll
;         for (int r = 0; r < 16; ++r) g[r] = 0.f;
;         const ALAS unsigned char* kp = lds + 37888 + (r32 & 15) * ROWB + hi * 16;
; #pragma unroll
;         for (int d0 = 0; d0 < 4; ++d0) {
;             const bf16x8 ah = *(const ALAS bf16x8*)(kp + d0 * 32), al = *(const ALAS bf16x8*)(kp + 2304 + d0 * 32);
;             g = __builtin_amdgcn_mfma_f32_32x32x16_bf16(ah, qf[d0], g, 0, 0, 0);
;             g = __builtin_amdgcn_mfma_f32_32x32x16_bf16(al, qf[d0], g, 0, 0, 0);
;         }
;         float gv[16];
; #pragma unroll
;         for (int r = 0; r < 8; ++r) { const float own = g[r], oth = __shfl_xor(own, 32); const int n0 = (r & 3) + 8 * (r >> 2);
.LBB0_520:
	s_bfe_u32 s6, s36, 0x40001
	s_lshl_b32 s4, s6, 8
	v_mov_b32_e32 v144, s4
	s_cmp_gt_i32 s38, 3
	s_cbranch_scc1 .LBB0_524
	v_add_u32_e32 v0, s4, v10
	s_waitcnt lgkmcnt(0)
	v_ashrrev_i32_e32 v1, 31, v0
	v_lshl_add_u64 v[0:1], v[0:1], 2, s[96:97]
	global_load_dword v21, v[0:1], off
.LBB0_524:
	s_ashr_i32 s7, s36, 7
	s_and_b32 s0, s36, 1
	s_and_b32 s7, s7, -4
	s_bfe_u32 s10, s36, 0x30005
	s_or_b32 s0, s7, s0
	s_lshl_b32 s4, s10, 12
	s_and_b32 s1, s36, 0x100
	s_xor_b32 s7, s0, 3
	v_ashrrev_i32_e32 v6, 5, v10
	v_lshlrev_b32_e32 v2, 1, v10
	s_cmp_eq_u32 s1, 0
	v_and_b32_e32 v7, 62, v2
	v_lshl_add_u32 v2, s10, 4, v6
	s_cselect_b32 s37, s0, s7
	s_waitcnt lgkmcnt(0)
	v_ashrrev_i32_e32 v3, 31, v2
	v_readlane_b32 s0, v255, 14
	v_lshlrev_b64 v[2:3], 13, v[2:3]
	v_readlane_b32 s1, v255, 15
	s_waitcnt lgkmcnt(0)
	v_lshl_add_u64 v[0:1], v[144:145], 2, s[96:97]
	v_lshlrev_b32_e32 v144, 2, v7
	v_lshl_add_u64 v[2:3], s[0:1], 0, v[2:3]
	s_lshl_b32 s0, s6, 8
	s_mov_b32 s1, s5
	v_lshl_add_u64 v[2:3], v[2:3], 0, s[0:1]
	v_lshl_add_u64 v[2:3], v[2:3], 0, v[144:145]
	s_movk_i32 s0, 0x1000
	v_add_co_u32_e32 v4, vcc, s0, v2
	s_mov_b64 s[74:75], s[96:97]
	s_nop 0
	v_addc_co_u32_e32 v5, vcc, 0, v3, vcc
	global_load_dwordx2 v[12:13], v[2:3], off
	global_load_dwordx2 v[14:15], v[4:5], off
	s_lshl_b32 s96, s37, 8
	s_lshl_b32 s0, s38, 5
	v_and_b32_e32 v11, 31, v10
	s_add_i32 s1, s0, s96
	v_or_b32_e32 v90, s1, v11
	v_ashrrev_i32_e32 v91, 31, v90
	v_lshl_add_u64 v[88:89], v[90:91], 0, s[4:5]
	v_lshlrev_b64 v[2:3], 11, v[88:89]
	v_bfe_u32 v48, v10, 5, 1
	v_lshl_add_u64 v[2:3], s[80:81], 0, v[2:3]
	s_lshl_b32 s8, s6, 7
	s_mov_b32 s9, s5
	v_lshl_add_u64 v[2:3], v[2:3], 0, s[8:9]
	v_lshlrev_b32_e32 v144, 4, v48
	v_lshl_add_u64 v[4:5], v[2:3], 0, v[144:145]
	global_load_dwordx4 v[64:67], v[4:5], off
	global_load_dwordx4 v[68:71], v[4:5], off offset:32
	global_load_dwordx4 v[72:75], v[4:5], off offset:64
	v_ashrrev_i32_e32 v8, 3, v10
	v_ashrrev_i32_e32 v9, 31, v8
	v_and_b32_e32 v2, 7, v10
	global_load_dword v99, v[0:1], off offset:1020
	s_movk_i32 s39, 0x90
	v_lshl_add_u64 v[0:1], v[8:9], 0, s[4:5]
	v_mul_lo_u32 v6, v6, s39
	v_lshlrev_b32_e32 v92, 4, v2
	v_lshlrev_b32_e32 v2, 1, v7
	v_lshlrev_b64 v[0:1], 11, v[0:1]
	s_lshl_b32 s58, s6, 6
	v_and_b32_e32 v3, 15, v10
	v_add3_u32 v9, 0, v6, v2
	v_lshl_add_u64 v[0:1], s[82:83], 0, v[0:1]
	v_add_u32_e32 v2, s58, v8
	v_mov_b32_e32 v93, v145
	v_mul_u32_u24_e32 v16, 0x90, v3
	v_lshl_add_u64 v[0:1], v[0:1], 0, s[8:9]
	v_ashrrev_i32_e32 v3, 31, v2
	s_ashr_i32 s97, s96, 31
	v_lshl_add_u64 v[94:95], v[0:1], 0, v[92:93]
	v_lshlrev_b64 v[0:1], 16, v[2:3]
	s_lshl_b64 s[6:7], s[96:97], 11
	v_lshl_add_u64 v[6:7], s[20:21], 0, v[0:1]
	v_lshl_add_u64 v[0:1], v[94:95], 0, s[6:7]
	global_load_dwordx4 v[0:3], v[0:1], off
	s_nop 0
	global_load_dwordx4 v[76:79], v[4:5], off offset:96
	v_add3_u32 v20, 0, v16, v144
	s_lshl_b32 s4, s10, 13
	v_lshl_add_u64 v[4:5], v[6:7], 0, s[4:5]
	v_lshl_add_u64 v[96:97], v[4:5], 0, v[92:93]
	v_lshl_add_u64 v[4:5], s[96:97], 1, v[96:97]
	global_load_dwordx4 v[4:7], v[4:5], off
	v_lshlrev_b32_e32 v98, 3, v48
	s_waitcnt vmcnt(7)
	s_cmp_gt_i32 s38, 3
	s_cbranch_scc1 .Lmoba_bias_done
	v_lshl_add_u32 v22, v10, 2, 0
	ds_write_b32 v22, v21 offset:36864
	ds_write_b32 v22, v21 offset:44032
	ds_write_b32 v22, v205 offset:43008
.Lmoba_bias_done:
	s_cmp_lt_i32 s37, 0
	v_pk_add_f32 v[12:13], v[12:13], v[14:15]
	s_nop 0
	v_cvt_pk_bf16_f32 v16, v12, v13
	v_lshlrev_b32_e32 v14, 16, v16
	v_and_b32_e32 v15, 0xffff0000, v16
	v_pk_add_f32 v[12:13], v[12:13], v[14:15] neg_lo:[0,1] neg_hi:[0,1]
	s_nop 0
	v_cvt_pk_bf16_f32 v12, v12, v13
	ds_write2st64_b32 v9, v16, v12 offset0:148 offset1:157
	s_waitcnt lgkmcnt(0)
	s_barrier
	ds_read_b128 v[12:15], v20 offset:37888
	s_waitcnt vmcnt(6) lgkmcnt(0)
	v_mfma_f32_32x32x16_bf16 v[32:47], v[12:15], v[64:67], 0
	ds_read_b128 v[12:15], v20 offset:40192
	v_xor_b32_e32 v9, 32, v203
	s_waitcnt lgkmcnt(0)
	v_mfma_f32_32x32x16_bf16 v[32:47], v[12:15], v[64:67], v[32:47]
	ds_read_b128 v[12:15], v20 offset:37920
	s_waitcnt vmcnt(5) lgkmcnt(0)
	v_mfma_f32_32x32x16_bf16 v[32:47], v[12:15], v[68:71], v[32:47]
	ds_read_b128 v[12:15], v20 offset:40224
	s_waitcnt lgkmcnt(0)
	v_mfma_f32_32x32x16_bf16 v[32:47], v[12:15], v[68:71], v[32:47]
	ds_read_b128 v[12:15], v20 offset:37952
	ds_read_b128 v[16:19], v20 offset:40256
	s_waitcnt vmcnt(4) lgkmcnt(1)
	v_mfma_f32_32x32x16_bf16 v[32:47], v[12:15], v[72:75], v[32:47]
	ds_read_b128 v[12:15], v20 offset:37984
	s_waitcnt lgkmcnt(1)
	v_mfma_f32_32x32x16_bf16 v[32:47], v[16:19], v[72:75], v[32:47]
	ds_read_b128 v[16:19], v20 offset:40288
	s_waitcnt vmcnt(1) lgkmcnt(1)
	v_mfma_f32_32x32x16_bf16 v[32:47], v[12:15], v[76:79], v[32:47]
	v_and_b32_e32 v12, 64, v203
	v_add_u32_e32 v12, 64, v12
	v_cmp_lt_i32_e32 vcc, v9, v12
	s_nop 1
	v_cndmask_b32_e32 v9, v203, v9, vcc
	v_lshlrev_b32_e32 v93, 2, v9
	s_waitcnt lgkmcnt(0)
	v_mfma_f32_32x32x16_bf16 v[32:47], v[16:19], v[76:79], v[32:47]
	s_nop 11
	ds_bpermute_b32 v42, v93, v32
	ds_bpermute_b32 v50, v93, v33
	ds_bpermute_b32 v49, v93, v34
	ds_bpermute_b32 v47, v93, v35
	ds_bpermute_b32 v46, v93, v36
	ds_bpermute_b32 v45, v93, v37
	ds_bpermute_b32 v43, v93, v38
	ds_bpermute_b32 v44, v93, v39
	s_cbranch_scc1 .LBB0_516
	v_mul_lo_u32 v104, v8, s39
	s_or_b32 s4, s96, 64
	v_add3_u32 v8, 0, v104, v92
	s_lshl_b64 s[6:7], s[4:5], 11
	ds_write_b128 v8, v[0:3]
	s_waitcnt vmcnt(0)
	ds_write_b128 v8, v[4:7] offset:9216
	v_lshl_add_u64 v[0:1], v[94:95], 0, s[6:7]
	s_mov_b32 s97, s5
	s_waitcnt lgkmcnt(0)
	s_barrier
; __device__ __forceinline__ void moba_unit(int b, int h, int j, const bf16_t* Q, const bf16_t* K, const bf16_t* VT, bf16_t* O, const float* biasd, const float* kmean, ALAS unsigned char* lds) {
;     ...
;         if (t + 1 < NT) { const int t1 = t + 1; const int kb1 = (t1 < 4) ? (256 * j + 64 * t1) : (64 * (t1 - 4));
;             kr = *(const u32x4*)(kg + (size_t)kb1 * 1024); vr = *(const u32x4*)(vg + kb1); }
;         const bool own = t < 4; const int n = own ? j : ((t - 4) >> 2); const int kbase = own ? (256 * j + 64 * t) : (64 * (t - 4));
;         const bool sel = own ? true : (((selmask >> n) & 1u) != 0u);
;         const bool active = own ? (64 * t <= 32 * wid + 31) : (__any(sel) != 0);
;         if (active) {
;             const bool nearb = (q0 - (kbase + 63)) < 128;
;             f32x16 s0, s1; const float ci = sel ? ((nearb ? 0.f : cb) - mref) : NEG;
;             qk_tile(s0, s1, ci, buf, qf, r32, hi);
;             if (nearb) near_bias(s0, s1, bt, qpos, kbase, hi);
	v_lshl_add_u64 v[2:3], s[96:97], 1, v[96:97]
	global_load_dwordx4 v[80:83], v[0:1], off
	global_load_dwordx4 v[84:87], v[2:3], off offset:128
	v_lshlrev_b32_e32 v1, 1, v11
	v_lshrrev_b32_e32 v2, 1, v10
	v_and_b32_e32 v0, 19, v10
	v_and_b32_e32 v1, 8, v1
	v_and_b32_e32 v2, 4, v2
	s_sub_i32 s4, s1, 63
	v_or3_b32 v0, v2, v0, v1
	v_mul_u32_u24_e32 v105, 0x90, v0
	s_cmp_lt_i32 s38, 0
	v_mul_u32_u24_e32 v106, 0x90, v11
	s_cbranch_scc1 .LBB0_530
	v_add3_u32 v1, 0, v105, v144
	ds_read_b128 v[52:55], v1 offset:0
	ds_read_b128 v[56:59], v1 offset:4608
	ds_read_b128 v[60:63], v1 offset:32
	ds_read_b128 v[100:103], v1 offset:4640
	ds_read_b128 v[108:111], v1 offset:64
	ds_read_b128 v[112:115], v1 offset:4672
	s_sub_i32 s1, s4, s96
	ds_read_b128 v[116:119], v1 offset:96
	s_cmpk_gt_i32 s1, 0x7f
	ds_read_b128 v[120:123], v1 offset:4704
	s_cselect_b64 vcc, -1, 0
	v_cndmask_b32_e32 v0, 0, v99, vcc
	v_mov_b32_e32 v1, v0
	v_mov_b32_e32 v2, v0
	v_mov_b32_e32 v3, v0
	v_mov_b32_e32 v4, v0
	v_mov_b32_e32 v5, v0
	v_mov_b32_e32 v6, v0
	v_mov_b32_e32 v7, v0
	v_mov_b32_e32 v8, v0
	v_mov_b32_e32 v9, v0
	v_mov_b32_e32 v10, v0
	v_mov_b32_e32 v11, v0
	v_mov_b32_e32 v12, v0
	v_mov_b32_e32 v13, v0
	v_mov_b32_e32 v14, v0
	v_mov_b32_e32 v15, v0
	s_waitcnt lgkmcnt(6)
	s_nop 1
	v_mfma_f32_32x32x16_bf16 v[16:31], v[52:55], v[64:67], v[0:15]
	s_and_b64 vcc, exec, vcc
	v_mfma_f32_32x32x16_bf16 v[0:15], v[56:59], v[64:67], v[0:15]
	s_waitcnt lgkmcnt(4)
	v_mfma_f32_32x32x16_bf16 v[16:31], v[60:63], v[68:71], v[16:31]
	v_mfma_f32_32x32x16_bf16 v[0:15], v[100:103], v[68:71], v[0:15]
	s_waitcnt lgkmcnt(2)
	v_mfma_f32_32x32x16_bf16 v[16:31], v[108:111], v[72:75], v[16:31]
	v_mfma_f32_32x32x16_bf16 v[0:15], v[112:115], v[72:75], v[0:15]
	s_waitcnt lgkmcnt(0)
	v_mfma_f32_32x32x16_bf16 v[16:31], v[116:119], v[76:79], v[16:31]
	v_mfma_f32_32x32x16_bf16 v[0:15], v[120:123], v[76:79], v[0:15]
	s_cbranch_vccnz .LBB0_528
	v_or_b32_e32 v51, s96, v98
	v_xad_u32 v107, v51, -1, v90
	v_med3_i32 v52, v107, 0, v204
	v_lshl_add_u32 v53, v52, 2, 0
	v_max_i32_e32 v52, 32, v107
	v_subrev_u32_e32 v52, 32, v52
	v_min_u32_e32 v52, 0xff, v52
	v_or_b32_e32 v55, 2, v51
	v_lshl_add_u32 v54, v52, 2, 0
	v_or_b32_e32 v52, 3, v51
	v_sub_u32_e32 v123, v90, v55
	v_sub_u32_e32 v122, v90, v52
	v_med3_i32 v52, v123, 0, v204
	v_lshl_add_u32 v55, v52, 2, 0
	v_max_i32_e32 v52, 32, v123
	v_subrev_u32_e32 v52, 32, v52
	v_min_u32_e32 v52, 0xff, v52
	v_sub_u32_e32 v91, v90, v51
	v_lshl_add_u32 v56, v52, 2, 0
	v_max_i32_e32 v52, 32, v122
	v_max_i32_e32 v41, 32, v91
	v_subrev_u32_e32 v52, 32, v52
	v_subrev_u32_e32 v41, 32, v41
	v_min_u32_e32 v52, 0xff, v52
	v_med3_i32 v40, v91, 0, v204
	v_min_u32_e32 v41, 0xff, v41
	v_lshl_add_u32 v57, v52, 2, 0
	v_med3_i32 v52, v122, 0, v204
	v_lshl_add_u32 v40, v40, 2, 0
	v_lshl_add_u32 v41, v41, 2, 0
	v_lshl_add_u32 v58, v52, 2, 0
	ds_read_b32 v52, v40 offset:36864
	ds_read_b32 v40, v41 offset:36864
	ds_read_b32 v53, v53 offset:36864
	ds_read_b32 v41, v54 offset:36864
	ds_read_b32 v54, v55 offset:36864
	ds_read_b32 v56, v56 offset:36864
	ds_read_b32 v57, v57 offset:36864
	ds_read_b32 v55, v58 offset:36864
	v_or_b32_e32 v58, 5, v51
	v_sub_u32_e32 v124, v90, v58
	v_max_i32_e32 v60, 32, v124
	v_subrev_u32_e32 v60, 32, v60
	v_min_u32_e32 v60, 0xff, v60
	v_lshl_add_u32 v61, v60, 2, 0
	v_med3_i32 v60, v124, 0, v204
	v_or_b32_e32 v63, 6, v51
	v_lshl_add_u32 v62, v60, 2, 0
	v_or_b32_e32 v60, 7, v51
	v_sub_u32_e32 v127, v90, v63
	v_sub_u32_e32 v126, v90, v60
	v_med3_i32 v60, v127, 0, v204
	v_lshl_add_u32 v63, v60, 2, 0
	v_max_i32_e32 v60, 32, v127
	v_subrev_u32_e32 v60, 32, v60
	v_or_b32_e32 v59, 4, v51
	v_min_u32_e32 v60, 0xff, v60
	v_sub_u32_e32 v125, v90, v59
	v_lshl_add_u32 v100, v60, 2, 0
	v_max_i32_e32 v60, 32, v126
	v_max_i32_e32 v59, 32, v125
	v_subrev_u32_e32 v60, 32, v60
	v_subrev_u32_e32 v59, 32, v59
	v_min_u32_e32 v60, 0xff, v60
	v_med3_i32 v58, v125, 0, v204
	v_min_u32_e32 v59, 0xff, v59
	v_lshl_add_u32 v101, v60, 2, 0
	v_med3_i32 v60, v126, 0, v204
	v_lshl_add_u32 v58, v58, 2, 0
	v_lshl_add_u32 v59, v59, 2, 0
	v_lshl_add_u32 v102, v60, 2, 0
	ds_read_b32 v58, v58 offset:36864
	ds_read_b32 v60, v59 offset:36864
	ds_read_b32 v61, v61 offset:36864
	ds_read_b32 v59, v62 offset:36864
	ds_read_b32 v62, v63 offset:36864
	ds_read_b32 v100, v100 offset:36864
	ds_read_b32 v101, v101 offset:36864
	ds_read_b32 v63, v102 offset:36864
	v_or_b32_e32 v102, 17, v51
	v_sub_u32_e32 v128, v90, v102
	v_max_i32_e32 v108, 32, v128
	v_subrev_u32_e32 v108, 32, v108
	v_min_u32_e32 v108, 0xff, v108
	v_lshl_add_u32 v109, v108, 2, 0
	v_med3_i32 v108, v128, 0, v204
	v_or_b32_e32 v111, 18, v51
	v_lshl_add_u32 v110, v108, 2, 0
	v_or_b32_e32 v108, 19, v51
	v_sub_u32_e32 v131, v90, v111
	v_sub_u32_e32 v130, v90, v108
	v_med3_i32 v108, v131, 0, v204
	v_lshl_add_u32 v111, v108, 2, 0
	v_max_i32_e32 v108, 32, v131
	v_subrev_u32_e32 v108, 32, v108
	v_or_b32_e32 v103, 16, v51
	v_min_u32_e32 v108, 0xff, v108
	v_sub_u32_e32 v129, v90, v103
	v_lshl_add_u32 v112, v108, 2, 0
	v_max_i32_e32 v108, 32, v130
	v_max_i32_e32 v103, 32, v129
	v_subrev_u32_e32 v108, 32, v108
	v_subrev_u32_e32 v103, 32, v103
	v_min_u32_e32 v108, 0xff, v108
	v_med3_i32 v102, v129, 0, v204
	v_min_u32_e32 v103, 0xff, v103
	v_lshl_add_u32 v113, v108, 2, 0
	v_med3_i32 v108, v130, 0, v204
	v_lshl_add_u32 v102, v102, 2, 0
	v_lshl_add_u32 v103, v103, 2, 0
	v_lshl_add_u32 v114, v108, 2, 0
	ds_read_b32 v102, v102 offset:36864
	ds_read_b32 v108, v103 offset:36864
	ds_read_b32 v109, v109 offset:36864
	ds_read_b32 v103, v110 offset:36864
	ds_read_b32 v110, v111 offset:36864
	ds_read_b32 v112, v112 offset:36864
	ds_read_b32 v113, v113 offset:36864
	ds_read_b32 v111, v114 offset:36864
	v_or_b32_e32 v114, 21, v51
	v_sub_u32_e32 v132, v90, v114
	v_max_i32_e32 v116, 32, v132
	v_subrev_u32_e32 v116, 32, v116
	v_min_u32_e32 v116, 0xff, v116
	v_lshl_add_u32 v117, v116, 2, 0
	v_med3_i32 v116, v132, 0, v204
	v_or_b32_e32 v115, 20, v51
	v_lshl_add_u32 v118, v116, 2, 0
	v_or_b32_e32 v116, 23, v51
	v_or_b32_e32 v51, 22, v51
	v_sub_u32_e32 v51, v90, v51
	v_sub_u32_e32 v134, v90, v116
	v_med3_i32 v116, v51, 0, v204
	v_lshl_add_u32 v119, v116, 2, 0
	v_max_i32_e32 v116, 32, v51
	v_subrev_u32_e32 v116, 32, v116
	v_sub_u32_e32 v133, v90, v115
	v_min_u32_e32 v116, 0xff, v116
	v_max_i32_e32 v115, 32, v133
	v_lshl_add_u32 v120, v116, 2, 0
	v_max_i32_e32 v116, 32, v134
	v_subrev_u32_e32 v115, 32, v115
	v_subrev_u32_e32 v116, 32, v116
	v_med3_i32 v114, v133, 0, v204
	v_min_u32_e32 v115, 0xff, v115
	v_min_u32_e32 v116, 0xff, v116
	v_lshl_add_u32 v114, v114, 2, 0
	v_lshl_add_u32 v115, v115, 2, 0
	v_lshl_add_u32 v121, v116, 2, 0
	v_med3_i32 v116, v134, 0, v204
	v_lshl_add_u32 v135, v116, 2, 0
	ds_read_b32 v114, v114 offset:36864
	ds_read_b32 v116, v115 offset:36864
	ds_read_b32 v117, v117 offset:36864
	ds_read_b32 v115, v118 offset:36864
	ds_read_b32 v118, v119 offset:36864
	ds_read_b32 v120, v120 offset:36864
	ds_read_b32 v121, v121 offset:36864
	ds_read_b32 v119, v135 offset:36864
	v_cmp_lt_i32_e32 vcc, -1, v134
	s_waitcnt lgkmcnt(4)
; __device__ __forceinline__ void near_bias(f32x16& s0, f32x16& s1, const ALAS float* bt, int qpos, int kbase, int hi) {
;     ...
;     for (int r = 0; r < 16; ++r) {
;         const int d0 = qpos - (kbase + (r & 7) + 8 * hi + 16 * (r >> 3)), d1 = d0 - 32;
;         const float b0 = bt[min(max(d0, 0), 255)], b1 = bt[min(max(d1, 0), 255)];
;         s0[r] = d0 < 0 ? NEG : s0[r] + b0; s1[r] = d1 < 0 ? NEG : s1[r] + b1;
;     }
	v_pk_add_f32 v[28:29], v[28:29], v[114:115]
	v_pk_add_f32 v[26:27], v[26:27], v[110:111]
	v_pk_add_f32 v[24:25], v[24:25], v[102:103]
	s_waitcnt lgkmcnt(0)
	v_pk_add_f32 v[30:31], v[30:31], v[118:119]
	v_pk_add_f32 v[22:23], v[22:23], v[62:63]
	v_cndmask_b32_e32 v31, v205, v31, vcc
	v_cmp_lt_i32_e32 vcc, -1, v51
	v_pk_add_f32 v[20:21], v[20:21], v[58:59]
	v_pk_add_f32 v[18:19], v[18:19], v[54:55]
	v_cndmask_b32_e32 v30, v205, v30, vcc
	v_cmp_lt_i32_e32 vcc, -1, v132
	v_pk_add_f32 v[16:17], v[16:17], v[52:53]
	v_pk_add_f32 v[14:15], v[14:15], v[120:121]
	v_cndmask_b32_e32 v29, v205, v29, vcc
	v_cmp_lt_i32_e32 vcc, -1, v133
	v_pk_add_f32 v[12:13], v[12:13], v[116:117]
	v_pk_add_f32 v[10:11], v[10:11], v[112:113]
	v_cndmask_b32_e32 v28, v205, v28, vcc
	v_cmp_lt_i32_e32 vcc, -1, v130
	v_pk_add_f32 v[8:9], v[8:9], v[108:109]
	v_pk_add_f32 v[6:7], v[6:7], v[100:101]
	v_cndmask_b32_e32 v27, v205, v27, vcc
	v_cmp_lt_i32_e32 vcc, -1, v131
	v_pk_add_f32 v[4:5], v[4:5], v[60:61]
	v_pk_add_f32 v[2:3], v[2:3], v[56:57]
	v_cndmask_b32_e32 v26, v205, v26, vcc
	v_cmp_lt_i32_e32 vcc, -1, v128
	v_pk_add_f32 v[0:1], v[0:1], v[40:41]
	s_nop 0
	v_cndmask_b32_e32 v25, v205, v25, vcc
	v_cmp_lt_i32_e32 vcc, -1, v129
	s_nop 1
	v_cndmask_b32_e32 v24, v205, v24, vcc
	v_cmp_lt_i32_e32 vcc, -1, v126
	s_nop 1
	v_cndmask_b32_e32 v23, v205, v23, vcc
	v_cmp_lt_i32_e32 vcc, -1, v127
	s_nop 1
	v_cndmask_b32_e32 v22, v205, v22, vcc
	v_cmp_lt_i32_e32 vcc, -1, v124
	s_nop 1
	v_cndmask_b32_e32 v21, v205, v21, vcc
	v_cmp_lt_i32_e32 vcc, -1, v125
	s_nop 1
	v_cndmask_b32_e32 v20, v205, v20, vcc
	v_cmp_lt_i32_e32 vcc, -1, v122
	s_nop 1
	v_cndmask_b32_e32 v19, v205, v19, vcc
	v_cmp_lt_i32_e32 vcc, -1, v123
	s_nop 1
	v_cndmask_b32_e32 v18, v205, v18, vcc
	v_cmp_lt_i32_e32 vcc, -1, v107
	s_nop 1
	v_cndmask_b32_e32 v17, v205, v17, vcc
	v_cmp_lt_i32_e32 vcc, -1, v91
	s_nop 1
	v_cndmask_b32_e32 v16, v205, v16, vcc
	v_cmp_lt_i32_e32 vcc, 31, v134
	s_nop 1
	v_cndmask_b32_e32 v15, v205, v15, vcc
	v_cmp_lt_i32_e32 vcc, 31, v51
	s_nop 1
	v_cndmask_b32_e32 v14, v205, v14, vcc
	v_cmp_lt_i32_e32 vcc, 31, v132
	s_nop 1
	v_cndmask_b32_e32 v13, v205, v13, vcc
	v_cmp_lt_i32_e32 vcc, 31, v133
	s_nop 1
	v_cndmask_b32_e32 v12, v205, v12, vcc
	v_cmp_lt_i32_e32 vcc, 31, v130
	s_nop 1
	v_cndmask_b32_e32 v11, v205, v11, vcc
	v_cmp_lt_i32_e32 vcc, 31, v131
	s_nop 1
	v_cndmask_b32_e32 v10, v205, v10, vcc
	v_cmp_lt_i32_e32 vcc, 31, v128
	s_nop 1
	v_cndmask_b32_e32 v9, v205, v9, vcc
	v_cmp_lt_i32_e32 vcc, 31, v129
	s_nop 1
	v_cndmask_b32_e32 v8, v205, v8, vcc
	v_cmp_lt_i32_e32 vcc, 31, v126
	s_nop 1
	v_cndmask_b32_e32 v7, v205, v7, vcc
	v_cmp_lt_i32_e32 vcc, 31, v127
	s_nop 1
	v_cndmask_b32_e32 v6, v205, v6, vcc
	v_cmp_lt_i32_e32 vcc, 31, v124
	s_nop 1
	v_cndmask_b32_e32 v5, v205, v5, vcc
	v_cmp_lt_i32_e32 vcc, 31, v125
	s_nop 1
	v_cndmask_b32_e32 v4, v205, v4, vcc
	v_cmp_lt_i32_e32 vcc, 31, v122
	s_nop 1
	v_cndmask_b32_e32 v3, v205, v3, vcc
	v_cmp_lt_i32_e32 vcc, 31, v123
	s_nop 1
	v_cndmask_b32_e32 v2, v205, v2, vcc
	v_cmp_lt_i32_e32 vcc, 31, v107
	s_nop 1
	v_cndmask_b32_e32 v1, v205, v1, vcc
	v_cmp_lt_i32_e32 vcc, 31, v91
	s_nop 1
	v_cndmask_b32_e32 v0, v205, v0, vcc
